# fold log2e into gate weights and 1/log2e into up weights at the P0 transpose; SwiGLU epilogue drops 64 v_mul per tile (v_exp of negated gate)
# baseline (speedup 1.0000x reference)
.LBB0_43:
	s_cmp_lg_u32 s33, 1
	s_cbranch_scc1 .Lgu_scale_a
	v_mov_b32_e32 v73, 0x3f317218
	s_cmpk_gt_i32 s14, 0xaff
	s_cbranch_scc1 .Lgu_scale_a
	v_mov_b32_e32 v73, 0x3fb8aa3b

.LBB0_59:
	s_cmp_lg_u32 s40, 1
	s_cbranch_scc1 .Lgu_scale_b
	v_mov_b32_e32 v81, 0x3f317218
	s_cmpk_gt_i32 s22, 0xaff
	s_cbranch_scc1 .Lgu_scale_b
	v_mov_b32_e32 v81, 0x3fb8aa3b

.LBB0_886:
	v_exp_f32_e64 v151, -v126
	v_exp_f32_e64 v152, -v127
	v_exp_f32_e64 v153, -v128
	v_exp_f32_e64 v154, -v129
	v_exp_f32_e64 v155, -v122
	v_exp_f32_e64 v156, -v123
	v_exp_f32_e64 v157, -v124
	v_lshl_add_u32 v150, s91, 8, v142
	v_exp_f32_e64 v158, -v125
	v_mov_b64_e32 v[140:141], s[4:5]
	v_lshl_add_u32 v146, s90, 7, v144
	v_mad_i64_i32 v[148:149], s[12:13], v150, s62, v[140:141]
	v_ashrrev_i32_e32 v147, 31, v146
	v_add_f32_e32 v151, 1.0, v151
	v_mul_f32_e32 v118, v126, v118
	v_add_f32_e32 v126, 1.0, v152
	v_mul_f32_e32 v119, v127, v119
	v_add_f32_e32 v127, 1.0, v153
	v_mul_f32_e32 v120, v128, v120
	v_add_f32_e32 v128, 1.0, v154
	v_mul_f32_e32 v121, v129, v121
	v_add_f32_e32 v129, 1.0, v155
	v_mul_f32_e32 v114, v122, v114
	v_add_f32_e32 v122, 1.0, v156
	v_mul_f32_e32 v115, v123, v115
	v_add_f32_e32 v123, 1.0, v157
	v_mul_f32_e32 v116, v124, v116
	v_add_f32_e32 v124, 1.0, v158
	v_mul_f32_e32 v117, v125, v117
	v_rcp_f32_e32 v125, v151
	v_rcp_f32_e32 v126, v126
	v_rcp_f32_e32 v127, v127
	v_rcp_f32_e32 v128, v128
	v_rcp_f32_e32 v129, v129
	v_rcp_f32_e32 v122, v122
	v_rcp_f32_e32 v123, v123
	v_rcp_f32_e32 v124, v124
	v_mul_f32_e32 v118, v125, v118
	v_mul_f32_e32 v125, v127, v120
	v_mul_f32_e32 v127, v129, v114
	v_mul_f32_e32 v122, v122, v115
	v_lshlrev_b64 v[114:115], 1, v[146:147]
	v_mul_f32_e32 v119, v126, v119
	v_mul_f32_e32 v126, v128, v121
	v_mul_f32_e32 v123, v123, v116
	v_lshl_add_u64 v[120:121], v[148:149], 0, v[114:115]
	v_cvt_pk_bf16_f32 v116, v118, v119
	v_mul_f32_e32 v124, v124, v117
	v_cvt_pk_bf16_f32 v117, v125, v126
	v_cvt_pk_bf16_f32 v118, v127, v122
	v_cvt_pk_bf16_f32 v119, v123, v124
	global_store_dwordx4 v[120:121], v[116:119], off
	s_nop 1
	v_exp_f32_e64 v118, -v110
	v_exp_f32_e64 v119, -v111
	v_exp_f32_e64 v120, -v112
	v_exp_f32_e64 v121, -v113
	v_exp_f32_e64 v122, -v106
	v_exp_f32_e64 v123, -v107
	v_exp_f32_e64 v124, -v108
	v_exp_f32_e64 v125, -v109
	v_or_b32_e32 v116, 16, v150
	v_mad_i64_i32 v[116:117], s[12:13], v116, s62, v[140:141]
	v_add_f32_e32 v118, 1.0, v118
	v_mul_f32_e32 v102, v110, v102
	v_add_f32_e32 v110, 1.0, v119
	v_mul_f32_e32 v103, v111, v103
	v_add_f32_e32 v111, 1.0, v120
	v_mul_f32_e32 v104, v112, v104
	v_add_f32_e32 v112, 1.0, v121
	v_mul_f32_e32 v105, v113, v105
	v_add_f32_e32 v113, 1.0, v122
	v_mul_f32_e32 v98, v106, v98
	v_add_f32_e32 v106, 1.0, v123
	v_mul_f32_e32 v99, v107, v99
	v_add_f32_e32 v107, 1.0, v124
	v_mul_f32_e32 v100, v108, v100
	v_add_f32_e32 v108, 1.0, v125
	v_mul_f32_e32 v101, v109, v101
	v_rcp_f32_e32 v109, v118
	v_rcp_f32_e32 v110, v110
	v_rcp_f32_e32 v111, v111
	v_rcp_f32_e32 v112, v112
	v_rcp_f32_e32 v113, v113
	v_rcp_f32_e32 v106, v106
	v_rcp_f32_e32 v107, v107
	v_rcp_f32_e32 v108, v108
	v_mul_f32_e32 v109, v109, v102
	v_mul_f32_e32 v110, v110, v103
	v_mul_f32_e32 v104, v111, v104
	v_mul_f32_e32 v111, v113, v98
	v_mul_f32_e32 v101, v108, v101
	v_lshl_add_u64 v[102:103], v[116:117], 0, v[114:115]
	v_cvt_pk_bf16_f32 v98, v109, v110
	v_mul_f32_e32 v105, v112, v105
	v_mul_f32_e32 v106, v106, v99
	v_mul_f32_e32 v107, v107, v100
	v_cvt_pk_bf16_f32 v99, v104, v105
	v_cvt_pk_bf16_f32 v100, v111, v106
	v_cvt_pk_bf16_f32 v101, v107, v101
	global_store_dwordx4 v[102:103], v[98:101], off
	s_nop 1
	v_exp_f32_e64 v100, -v94
	v_exp_f32_e64 v101, -v95
	v_exp_f32_e64 v102, -v96
	v_exp_f32_e64 v103, -v97
	v_exp_f32_e64 v104, -v90
	v_exp_f32_e64 v105, -v91
	v_exp_f32_e64 v106, -v92
	v_exp_f32_e64 v107, -v93
	v_or_b32_e32 v98, 32, v150
	v_mad_i64_i32 v[98:99], s[12:13], v98, s62, v[140:141]
	v_add_f32_e32 v100, 1.0, v100
	v_mul_f32_e32 v86, v94, v86
	v_add_f32_e32 v94, 1.0, v101
	v_mul_f32_e32 v87, v95, v87
	v_add_f32_e32 v95, 1.0, v102
	v_mul_f32_e32 v88, v96, v88
	v_add_f32_e32 v96, 1.0, v103
	v_mul_f32_e32 v89, v97, v89
	v_add_f32_e32 v97, 1.0, v104
	v_mul_f32_e32 v82, v90, v82
	v_add_f32_e32 v90, 1.0, v105
	v_mul_f32_e32 v83, v91, v83
	v_add_f32_e32 v91, 1.0, v106
	v_mul_f32_e32 v84, v92, v84
	v_add_f32_e32 v92, 1.0, v107
	v_mul_f32_e32 v85, v93, v85
	v_rcp_f32_e32 v93, v100
	v_rcp_f32_e32 v94, v94
	v_rcp_f32_e32 v95, v95
	v_rcp_f32_e32 v96, v96
	v_rcp_f32_e32 v97, v97
	v_rcp_f32_e32 v90, v90
	v_rcp_f32_e32 v91, v91
	v_rcp_f32_e32 v92, v92
	v_mul_f32_e32 v93, v93, v86
	v_mul_f32_e32 v94, v94, v87
	v_mul_f32_e32 v88, v95, v88
	v_mul_f32_e32 v95, v97, v82
	v_mul_f32_e32 v85, v92, v85
	v_lshl_add_u64 v[86:87], v[98:99], 0, v[114:115]
	v_cvt_pk_bf16_f32 v82, v93, v94
	v_mul_f32_e32 v89, v96, v89
	v_mul_f32_e32 v90, v90, v83
	v_mul_f32_e32 v91, v91, v84
	v_cvt_pk_bf16_f32 v83, v88, v89
	v_cvt_pk_bf16_f32 v84, v95, v90
	v_cvt_pk_bf16_f32 v85, v91, v85
	global_store_dwordx4 v[86:87], v[82:85], off
	s_nop 1
	v_exp_f32_e64 v84, -v78
	v_exp_f32_e64 v85, -v79
	v_exp_f32_e64 v86, -v80
	v_exp_f32_e64 v87, -v81
	v_exp_f32_e64 v88, -v74
	v_exp_f32_e64 v89, -v75
	v_exp_f32_e64 v90, -v76
	v_exp_f32_e64 v91, -v77
	v_or_b32_e32 v82, 48, v150
	v_mad_i64_i32 v[82:83], s[12:13], v82, s62, v[140:141]
	v_add_f32_e32 v84, 1.0, v84
	v_mul_f32_e32 v70, v78, v70
	v_add_f32_e32 v78, 1.0, v85
	v_mul_f32_e32 v71, v79, v71
	v_add_f32_e32 v79, 1.0, v86
	v_mul_f32_e32 v72, v80, v72
	v_add_f32_e32 v80, 1.0, v87
	v_mul_f32_e32 v73, v81, v73
	v_add_f32_e32 v81, 1.0, v88
	v_mul_f32_e32 v66, v74, v66
	v_add_f32_e32 v74, 1.0, v89
	v_mul_f32_e32 v67, v75, v67
	v_add_f32_e32 v75, 1.0, v90
	v_mul_f32_e32 v68, v76, v68
	v_add_f32_e32 v76, 1.0, v91
	v_mul_f32_e32 v69, v77, v69
	v_rcp_f32_e32 v77, v84
	v_rcp_f32_e32 v78, v78
	v_rcp_f32_e32 v79, v79
	v_rcp_f32_e32 v80, v80
	v_rcp_f32_e32 v81, v81
	v_rcp_f32_e32 v74, v74
	v_rcp_f32_e32 v75, v75
	v_rcp_f32_e32 v76, v76
	v_mul_f32_e32 v77, v77, v70
	v_mul_f32_e32 v78, v78, v71
	v_mul_f32_e32 v72, v79, v72
	v_mul_f32_e32 v79, v81, v66
	v_mul_f32_e32 v69, v76, v69
	v_lshl_add_u64 v[70:71], v[82:83], 0, v[114:115]
	v_cvt_pk_bf16_f32 v66, v77, v78
	v_mul_f32_e32 v73, v80, v73
	v_mul_f32_e32 v74, v74, v67
	v_mul_f32_e32 v75, v75, v68
	v_cvt_pk_bf16_f32 v67, v72, v73
	v_cvt_pk_bf16_f32 v68, v79, v74
	v_cvt_pk_bf16_f32 v69, v75, v69
	global_store_dwordx4 v[70:71], v[66:69], off
	s_nop 1
	v_exp_f32_e64 v68, -v62
	v_exp_f32_e64 v69, -v63
	v_exp_f32_e64 v70, -v64
	v_exp_f32_e64 v71, -v65
	v_exp_f32_e64 v72, -v58
	v_exp_f32_e64 v73, -v59
	v_exp_f32_e64 v74, -v60
	v_exp_f32_e64 v75, -v61
	v_add_u32_e32 v66, 0x80, v150
	v_mad_i64_i32 v[66:67], s[12:13], v66, s62, v[140:141]
	v_add_f32_e32 v68, 1.0, v68
	v_mul_f32_e32 v54, v62, v54
	v_add_f32_e32 v62, 1.0, v69
	v_mul_f32_e32 v55, v63, v55
	v_add_f32_e32 v63, 1.0, v70
	v_mul_f32_e32 v56, v64, v56
	v_add_f32_e32 v64, 1.0, v71
	v_mul_f32_e32 v57, v65, v57
	v_add_f32_e32 v65, 1.0, v72
	v_mul_f32_e32 v50, v58, v50
	v_add_f32_e32 v58, 1.0, v73
	v_mul_f32_e32 v51, v59, v51
	v_add_f32_e32 v59, 1.0, v74
	v_mul_f32_e32 v52, v60, v52
	v_add_f32_e32 v60, 1.0, v75
	v_mul_f32_e32 v53, v61, v53
	v_rcp_f32_e32 v61, v68
	v_rcp_f32_e32 v62, v62
	v_rcp_f32_e32 v63, v63
	v_rcp_f32_e32 v64, v64
	v_rcp_f32_e32 v65, v65
	v_rcp_f32_e32 v58, v58
	v_rcp_f32_e32 v59, v59
	v_rcp_f32_e32 v60, v60
	v_mul_f32_e32 v61, v61, v54
	v_mul_f32_e32 v62, v62, v55
	v_mul_f32_e32 v56, v63, v56
	v_mul_f32_e32 v63, v65, v50
	v_mul_f32_e32 v53, v60, v53
	v_lshl_add_u64 v[54:55], v[66:67], 0, v[114:115]
	v_cvt_pk_bf16_f32 v50, v61, v62
	v_mul_f32_e32 v57, v64, v57
	v_mul_f32_e32 v58, v58, v51
	v_mul_f32_e32 v59, v59, v52
	v_cvt_pk_bf16_f32 v51, v56, v57
	v_cvt_pk_bf16_f32 v52, v63, v58
	v_cvt_pk_bf16_f32 v53, v59, v53
	global_store_dwordx4 v[54:55], v[50:53], off
	s_nop 1
	v_exp_f32_e64 v52, -v46
	v_exp_f32_e64 v53, -v47
	v_exp_f32_e64 v54, -v48
	v_exp_f32_e64 v55, -v49
	v_exp_f32_e64 v56, -v42
	v_exp_f32_e64 v57, -v43
	v_exp_f32_e64 v58, -v44
	v_exp_f32_e64 v59, -v45
	v_add_u32_e32 v50, 0x90, v150
	v_mad_i64_i32 v[50:51], s[12:13], v50, s62, v[140:141]
	v_add_f32_e32 v52, 1.0, v52
	v_mul_f32_e32 v38, v46, v38
	v_add_f32_e32 v46, 1.0, v53
	v_mul_f32_e32 v39, v47, v39
	v_add_f32_e32 v47, 1.0, v54
	v_mul_f32_e32 v40, v48, v40
	v_add_f32_e32 v48, 1.0, v55
	v_mul_f32_e32 v41, v49, v41
	v_add_f32_e32 v49, 1.0, v56
	v_mul_f32_e32 v34, v42, v34
	v_add_f32_e32 v42, 1.0, v57
	v_mul_f32_e32 v35, v43, v35
	v_add_f32_e32 v43, 1.0, v58
	v_mul_f32_e32 v36, v44, v36
	v_add_f32_e32 v44, 1.0, v59
	v_mul_f32_e32 v37, v45, v37
	v_rcp_f32_e32 v45, v52
	v_rcp_f32_e32 v46, v46
	v_rcp_f32_e32 v47, v47
	v_rcp_f32_e32 v48, v48
	v_rcp_f32_e32 v49, v49
	v_rcp_f32_e32 v42, v42
	v_rcp_f32_e32 v43, v43
	v_rcp_f32_e32 v44, v44
	v_mul_f32_e32 v45, v45, v38
	v_mul_f32_e32 v46, v46, v39
	v_mul_f32_e32 v40, v47, v40
	v_mul_f32_e32 v47, v49, v34
	v_mul_f32_e32 v37, v44, v37
	v_lshl_add_u64 v[38:39], v[50:51], 0, v[114:115]
	v_cvt_pk_bf16_f32 v34, v45, v46
	v_mul_f32_e32 v41, v48, v41
	v_mul_f32_e32 v42, v42, v35
	v_mul_f32_e32 v43, v43, v36
	v_cvt_pk_bf16_f32 v35, v40, v41
	v_cvt_pk_bf16_f32 v36, v47, v42
	v_cvt_pk_bf16_f32 v37, v43, v37
	global_store_dwordx4 v[38:39], v[34:37], off
	s_nop 1
	v_exp_f32_e64 v36, -v30
	v_exp_f32_e64 v37, -v31
	v_exp_f32_e64 v38, -v32
	v_exp_f32_e64 v39, -v33
	v_exp_f32_e64 v40, -v26
	v_exp_f32_e64 v41, -v27
	v_exp_f32_e64 v42, -v28
	v_exp_f32_e64 v43, -v29
	v_add_u32_e32 v34, 0xa0, v150
	v_mad_i64_i32 v[34:35], s[12:13], v34, s62, v[140:141]
	v_add_f32_e32 v36, 1.0, v36
	v_mul_f32_e32 v22, v30, v22
	v_add_f32_e32 v30, 1.0, v37
	v_mul_f32_e32 v23, v31, v23
	v_add_f32_e32 v31, 1.0, v38
	v_mul_f32_e32 v24, v32, v24
	v_add_f32_e32 v32, 1.0, v39
	v_mul_f32_e32 v25, v33, v25
	v_add_f32_e32 v33, 1.0, v40
	v_mul_f32_e32 v18, v26, v18
	v_add_f32_e32 v26, 1.0, v41
	v_mul_f32_e32 v19, v27, v19
	v_add_f32_e32 v27, 1.0, v42
	v_mul_f32_e32 v20, v28, v20
	v_add_f32_e32 v28, 1.0, v43
	v_mul_f32_e32 v21, v29, v21
	v_rcp_f32_e32 v29, v36
	v_rcp_f32_e32 v30, v30
	v_rcp_f32_e32 v31, v31
	v_rcp_f32_e32 v32, v32
	v_rcp_f32_e32 v33, v33
	v_rcp_f32_e32 v26, v26
	v_rcp_f32_e32 v27, v27
	v_rcp_f32_e32 v28, v28
	v_mul_f32_e32 v29, v29, v22
	v_mul_f32_e32 v30, v30, v23
	v_mul_f32_e32 v24, v31, v24
	v_mul_f32_e32 v31, v33, v18
	v_mul_f32_e32 v21, v28, v21
	v_lshl_add_u64 v[22:23], v[34:35], 0, v[114:115]
	v_cvt_pk_bf16_f32 v18, v29, v30
	v_mul_f32_e32 v25, v32, v25
	v_mul_f32_e32 v26, v26, v19
	v_mul_f32_e32 v27, v27, v20
	v_cvt_pk_bf16_f32 v19, v24, v25
	v_cvt_pk_bf16_f32 v20, v31, v26
	v_cvt_pk_bf16_f32 v21, v27, v21
	global_store_dwordx4 v[22:23], v[18:21], off
	s_nop 1
	v_exp_f32_e64 v20, -v14
	v_exp_f32_e64 v21, -v15
	v_exp_f32_e64 v22, -v16
	v_exp_f32_e64 v23, -v17
	v_exp_f32_e64 v24, -v10
	v_exp_f32_e64 v25, -v11
	v_exp_f32_e64 v26, -v12
	v_exp_f32_e64 v27, -v13
	v_add_u32_e32 v18, 0xb0, v150
	v_mad_i64_i32 v[18:19], s[12:13], v18, s62, v[140:141]
	v_add_f32_e32 v20, 1.0, v20
	v_mul_f32_e32 v6, v14, v6
	v_add_f32_e32 v14, 1.0, v21
	v_mul_f32_e32 v7, v15, v7
	v_add_f32_e32 v15, 1.0, v22
	v_mul_f32_e32 v8, v16, v8
	v_add_f32_e32 v16, 1.0, v23
	v_mul_f32_e32 v9, v17, v9
	v_add_f32_e32 v17, 1.0, v24
	v_mul_f32_e32 v2, v10, v2
	v_add_f32_e32 v10, 1.0, v25
	v_mul_f32_e32 v3, v11, v3
	v_add_f32_e32 v11, 1.0, v26
	v_mul_f32_e32 v4, v12, v4
	v_add_f32_e32 v12, 1.0, v27
	v_mul_f32_e32 v5, v13, v5
	v_rcp_f32_e32 v13, v20
	v_rcp_f32_e32 v14, v14
	v_rcp_f32_e32 v15, v15
	v_rcp_f32_e32 v16, v16
	v_rcp_f32_e32 v17, v17
	v_rcp_f32_e32 v10, v10
	v_rcp_f32_e32 v11, v11
	v_rcp_f32_e32 v12, v12
	v_readlane_b32 s84, v244, 24
	v_mul_f32_e32 v13, v13, v6
	v_mul_f32_e32 v14, v14, v7
	v_mul_f32_e32 v5, v12, v5
	v_lshl_add_u64 v[6:7], v[18:19], 0, v[114:115]
	s_cmp_eq_u32 s89, 10
	s_mov_b64 s[12:13], -1
	v_readlane_b32 s85, v244, 25
	v_mul_f32_e32 v8, v15, v8
	v_mul_f32_e32 v9, v16, v9
	v_mul_f32_e32 v15, v17, v2
	v_mul_f32_e32 v10, v10, v3
	v_mul_f32_e32 v11, v11, v4
	v_cvt_pk_bf16_f32 v2, v13, v14
	v_cvt_pk_bf16_f32 v3, v8, v9
	v_cvt_pk_bf16_f32 v4, v15, v10
	v_cvt_pk_bf16_f32 v5, v11, v5
	global_store_dwordx4 v[6:7], v[2:5], off
	s_cbranch_scc1 .LBB0_879
	s_andn2_b64 vcc, exec, s[2:3]
	s_cbranch_vccnz .LBB0_878
	s_barrier
	s_branch .LBB0_878
